# RWKV step B from registers + folded decay constant; mLSTM commit gate lanes first
# speedup vs baseline: 1.0077x; 1.0077x over previous
.Lrb2_p0:
	v_mul_f32_e32 v170, 0xbf60028a, v170
	v_mul_f32_e32 v171, 0xbf60028a, v171
	v_mul_f32_e32 v172, 0xbf60028a, v172
	v_mul_f32_e32 v173, 0xbf60028a, v173
	v_mul_f32_e32 v174, 0xbf60028a, v174
	v_mul_f32_e32 v175, 0xbf60028a, v175
	v_mul_f32_e32 v176, 0xbf60028a, v176
	v_mul_f32_e32 v177, 0xbf60028a, v177
	v_mul_f32_e32 v178, 0xbf60028a, v178
	v_mul_f32_e32 v179, 0xbf60028a, v179
	v_mul_f32_e32 v180, 0xbf60028a, v180
	v_mul_f32_e32 v181, 0xbf60028a, v181
	v_mul_f32_e32 v182, 0xbf60028a, v182
	v_mul_f32_e32 v183, 0xbf60028a, v183
	v_mul_f32_e32 v184, 0xbf60028a, v184
	v_mul_f32_e32 v185, 0xbf60028a, v185
	v_exp_f32_e32 v170, v170
	v_exp_f32_e32 v171, v171
	v_exp_f32_e32 v172, v172
	v_exp_f32_e32 v173, v173
	v_exp_f32_e32 v174, v174
	v_exp_f32_e32 v175, v175
	v_exp_f32_e32 v176, v176
	v_exp_f32_e32 v177, v177
	v_exp_f32_e32 v178, v178
	v_exp_f32_e32 v179, v179
	v_exp_f32_e32 v180, v180
	v_exp_f32_e32 v181, v181
	v_exp_f32_e32 v182, v182
	v_exp_f32_e32 v183, v183
	v_exp_f32_e32 v184, v184
	v_exp_f32_e32 v185, v185
	ds_write2_b32 v158, v170, v171 offset0:0 offset1:64
	ds_write2_b32 v158, v172, v173 offset0:128 offset1:192
	ds_write2_b32 v158, v174, v175 offset0:16 offset1:80
	ds_write2_b32 v158, v176, v177 offset0:144 offset1:208
	ds_write2_b32 v158, v178, v179 offset0:32 offset1:96
	ds_write2_b32 v158, v180, v181 offset0:160 offset1:224
	ds_write2_b32 v158, v182, v183 offset0:48 offset1:112
	ds_write2_b32 v158, v184, v185 offset0:176 offset1:240

.LBB0_829:
	s_or_b64 exec, exec, s[44:45]
	v_sub_co_u32_e64 v16, s[44:45], s77, 8
	s_waitcnt lgkmcnt(14)
	v_mov_b32_e32 v98, s77
	s_and_b64 s[74:75], s[44:45], exec
	v_cndmask_b32_e64 v16, v16, v98, s[44:45]
	s_cselect_b32 s78, 7, 0x1ff
	v_sub_u32_e32 v98, s78, v16
	v_cndmask_b32_e64 v16, v98, v16, s[4:5]
	s_waitcnt lgkmcnt(0)
	s_barrier
	ds_read_b32 v216, v145
	ds_read_b32 v217, v146 offset:64000
	ds_read_b32 v218, v147
	ds_read_b32 v219, v148 offset:65024
	ds_read_b32 v220, v149
	s_cselect_b32 s74, 0x4000, 0
	v_add_u32_e32 v169, s74, v150
	v_add_u32_e32 v170, v143, v135
	v_lshl_add_u32 v222, v16, 5, v169
	v_mov_b32_e32 v221, s89
	ds_read_b32 v171, v221
	ds_read_b128 v[98:101], v170 offset:54272
	ds_read_b128 v[102:105], v151
	ds_read_b128 v[172:175], v151 offset:16
	s_waitcnt lgkmcnt(4)
	v_add_f32_e32 v216, v216, v217
	v_add_f32_e32 v218, v218, v219
	v_max_f32_e32 v220, v220, v220
	v_max_f32_e64 v218, |v218|, v220
	v_rcp_f32_e32 v218, v218
	v_ashrrev_i32_e32 v223, 31, v222
	v_lshlrev_b64 v[222:223], 11, v[222:223]
	v_mul_f32_e32 v216, v216, v218
	v_lshl_add_u64 v[222:223], v[106:107], 0, v[222:223]
	v_cvt_pk_bf16_f32 v220, v216, v17
	global_store_short v[222:223], v220, off
	ds_read_b64_tr_b16 v[180:181], v178 offset:16896
	ds_read_b64_tr_b16 v[182:183], v178 offset:19008
	ds_read_b64_tr_b16 v[184:185], v178 offset:16928
	ds_read_b64_tr_b16 v[186:187], v178 offset:19040
	ds_read_b64_tr_b16 v[188:189], v178 offset:16960
	ds_read_b64_tr_b16 v[190:191], v178 offset:19072
	ds_read_b64_tr_b16 v[192:193], v178 offset:16992
	ds_read_b64_tr_b16 v[194:195], v178 offset:19104
	s_waitcnt lgkmcnt(8)
	v_lshlrev_b32_e32 v176, 16, v98
	v_add_f32_e32 v103, v171, v103
	v_mul_f32_e32 v103, 0x3fb8aa3b, v103
	v_exp_f32_e32 v103, v103
	v_add_f32_e32 v102, v171, v102
	v_mul_f32_e32 v102, 0x3fb8aa3b, v102
	v_and_b32_e32 v98, 0xffff0000, v98
	v_exp_f32_e32 v102, v102
	v_mul_f32_e32 v98, v103, v98
	v_add_f32_e32 v103, v171, v104
	v_mul_f32_e32 v103, 0x3fb8aa3b, v103
	v_exp_f32_e32 v103, v103
	v_mul_f32_e32 v102, v102, v176
	v_cvt_pk_bf16_f32 v98, v102, v98
	v_lshlrev_b32_e32 v102, 16, v99
	v_mul_f32_e32 v102, v103, v102
	v_add_f32_e32 v103, v171, v105
	v_mul_f32_e32 v103, 0x3fb8aa3b, v103
	v_exp_f32_e32 v103, v103
	v_and_b32_e32 v99, 0xffff0000, v99
	v_mul_f32_e32 v16, 0x3fb8aa3b, v171
	v_exp_f32_e32 v16, v16
	v_mul_f32_e32 v99, v103, v99
	v_add_f32_e32 v103, v171, v172
	v_mul_f32_e32 v103, 0x3fb8aa3b, v103
	v_exp_f32_e32 v103, v103
	v_cvt_pk_bf16_f32 v99, v102, v99
	v_lshlrev_b32_e32 v102, 16, v100
	v_and_b32_e32 v100, 0xffff0000, v100
	v_mul_f32_e32 v102, v103, v102
	v_add_f32_e32 v103, v171, v173
	v_mul_f32_e32 v103, 0x3fb8aa3b, v103
	v_exp_f32_e32 v103, v103
	v_pk_mul_f32 v[96:97], v[96:97], v[16:17] op_sel_hi:[1,0]
	v_pk_mul_f32 v[94:95], v[94:95], v[16:17] op_sel_hi:[1,0]
	v_pk_mul_f32 v[92:93], v[92:93], v[16:17] op_sel_hi:[1,0]
	v_mul_f32_e32 v100, v103, v100
	v_add_f32_e32 v103, v171, v174
	v_mul_f32_e32 v103, 0x3fb8aa3b, v103
	v_exp_f32_e32 v103, v103
	v_cvt_pk_bf16_f32 v100, v102, v100
	v_lshlrev_b32_e32 v102, 16, v101
	v_and_b32_e32 v101, 0xffff0000, v101
	v_mul_f32_e32 v102, v103, v102
	v_add_f32_e32 v103, v171, v175
	v_mul_f32_e32 v103, 0x3fb8aa3b, v103
	v_exp_f32_e32 v103, v103
	v_pk_mul_f32 v[90:91], v[90:91], v[16:17] op_sel_hi:[1,0]
	v_pk_mul_f32 v[88:89], v[88:89], v[16:17] op_sel_hi:[1,0]
	v_pk_mul_f32 v[86:87], v[86:87], v[16:17] op_sel_hi:[1,0]
	v_mul_f32_e32 v101, v103, v101
	v_cvt_pk_bf16_f32 v101, v102, v101
	v_pk_mul_f32 v[84:85], v[84:85], v[16:17] op_sel_hi:[1,0]
	v_pk_mul_f32 v[82:83], v[82:83], v[16:17] op_sel_hi:[1,0]
	s_waitcnt lgkmcnt(0)
	s_barrier
	s_nop 1
	v_mfma_f32_16x16x32_bf16 v[94:97], v[180:183], v[98:101], v[94:97]
	v_mfma_f32_16x16x32_bf16 v[90:93], v[184:187], v[98:101], v[90:93]
	v_mfma_f32_16x16x32_bf16 v[86:89], v[188:191], v[98:101], v[86:89]
	v_mfma_f32_16x16x32_bf16 v[82:85], v[192:195], v[98:101], v[82:85]
	s_and_saveexec_b64 s[74:75], s[10:11]
	s_cbranch_execz .LBB0_847

.LBB0_847:
	s_or_b64 exec, exec, s[74:75]
	s_waitcnt vmcnt(8)
	ds_write_b128 v155, v[46:49]
	s_waitcnt vmcnt(7)
	ds_write_b128 v156, v[50:53]
	s_waitcnt vmcnt(6)
	ds_write_b128 v157, v[54:57]
	s_waitcnt vmcnt(5)
	ds_write_b128 v158, v[58:61]
	s_waitcnt vmcnt(4)
	ds_write_b128 v159, v[66:69]
	s_waitcnt vmcnt(3)
	ds_write_b128 v160, v[70:73]
	s_waitcnt vmcnt(2)
	ds_write_b128 v161, v[74:77]
	s_waitcnt vmcnt(1)
	ds_write_b128 v177, v[78:81]
	v_cvt_pk_bf16_f32 v196, v94, v95
	v_cvt_pk_bf16_f32 v197, v96, v97
	ds_write_b64 v179, v[196:197] offset:55552
	v_cvt_pk_bf16_f32 v198, v90, v91
	v_cvt_pk_bf16_f32 v199, v92, v93
	ds_write_b64 v179, v[198:199] offset:55584
	v_cvt_pk_bf16_f32 v200, v86, v87
	v_cvt_pk_bf16_f32 v201, v88, v89
	ds_write_b64 v179, v[200:201] offset:55616
	v_cvt_pk_bf16_f32 v202, v82, v83
	v_cvt_pk_bf16_f32 v203, v84, v85
	ds_write_b64 v179, v[202:203] offset:55648
	s_waitcnt lgkmcnt(0)
	s_andn2_b64 vcc, exec, s[58:59]
	s_barrier
	s_cbranch_vccnz .LBB0_851
	s_cmp_lt_u32 s77, 6
	s_cselect_b32 s58, 2, -6
	s_cselect_b32 s59, 7, 0x1ff
	s_cselect_b32 s74, 0x4000, 0
	s_add_i32 s75, s58, s77
	s_sub_i32 s58, s59, s58
	s_add_i32 s58, s52, s58
	s_add_i32 s75, s75, 1
	s_add_i32 s79, s58, -1
	s_and_b64 s[58:59], s[4:5], exec
	s_cselect_b32 s58, s75, s79
	s_lshl_b32 s58, s58, 5
	s_add_i32 s74, s58, s74
	s_waitcnt vmcnt(8)
	v_add_u32_e32 v46, s74, v111
	v_add_u32_e32 v48, s74, v112
	s_waitcnt vmcnt(6)
	v_add_u32_e32 v54, s74, v113
	v_add_u32_e32 v56, s74, v114
	s_waitcnt vmcnt(4)
	v_add_u32_e32 v66, s74, v115
	v_add_u32_e32 v68, s74, v116
	s_waitcnt vmcnt(2)
	v_add_u32_e32 v74, s74, v117
	v_add_u32_e32 v76, s74, v121
	v_ashrrev_i32_e32 v47, 31, v46
	v_ashrrev_i32_e32 v49, 31, v48
	v_ashrrev_i32_e32 v55, 31, v54
	v_ashrrev_i32_e32 v57, 31, v56
	v_ashrrev_i32_e32 v67, 31, v66
	v_ashrrev_i32_e32 v69, 31, v68
	v_ashrrev_i32_e32 v75, 31, v74
	v_ashrrev_i32_e32 v77, 31, v76
	v_lshlrev_b64 v[46:47], 12, v[46:47]
	v_lshlrev_b64 v[48:49], 12, v[48:49]
	v_lshlrev_b64 v[54:55], 12, v[54:55]
	v_lshlrev_b64 v[56:57], 12, v[56:57]
	v_lshlrev_b64 v[66:67], 12, v[66:67]
	v_lshlrev_b64 v[68:69], 12, v[68:69]
	v_lshlrev_b64 v[74:75], 12, v[74:75]
	v_lshlrev_b64 v[76:77], 12, v[76:77]
	v_lshl_add_u64 v[46:47], v[108:109], 0, v[46:47]
	v_lshl_add_u64 v[50:51], v[108:109], 0, v[48:49]
	v_lshl_add_u64 v[54:55], v[108:109], 0, v[54:55]
	v_lshl_add_u64 v[58:59], v[108:109], 0, v[56:57]
	v_lshl_add_u64 v[66:67], v[108:109], 0, v[66:67]
	v_lshl_add_u64 v[70:71], v[108:109], 0, v[68:69]
	v_lshl_add_u64 v[74:75], v[108:109], 0, v[74:75]
	s_waitcnt vmcnt(1)
	v_lshl_add_u64 v[78:79], v[108:109], 0, v[76:77]
	global_load_dwordx4 v[46:49], v[46:47], off
	s_nop 0
	global_load_dwordx4 v[50:53], v[50:51], off
	s_nop 0
	global_load_dwordx4 v[54:57], v[54:55], off
	s_nop 0
	global_load_dwordx4 v[58:61], v[58:59], off
	s_nop 0
	global_load_dwordx4 v[66:69], v[66:67], off
	s_nop 0
	global_load_dwordx4 v[70:73], v[70:71], off
	s_nop 0
	global_load_dwordx4 v[74:77], v[74:75], off
	s_nop 0
	global_load_dwordx4 v[78:81], v[78:79], off
	s_and_saveexec_b64 s[58:59], s[10:11]
	s_cbranch_execz .LBB0_850
	v_add_u32_e32 v26, s74, v110
	v_ashrrev_i32_e32 v27, 31, v26
	v_lshl_add_u64 v[28:29], v[26:27], 4, s[48:49]
	v_lshlrev_b64 v[26:27], 11, v[26:27]
	v_lshl_add_u64 v[26:27], s[62:63], 0, v[26:27]
	global_load_dwordx4 v[62:65], v[26:27], off
	s_nop 0
	global_load_dwordx4 v[26:29], v[28:29], off

.LBB0_870:
	s_or_b64 exec, exec, s[58:59]
	s_waitcnt lgkmcnt(0)
	s_barrier
	ds_read_b32 v216, v145
	ds_read_b32 v217, v146 offset:64000
	ds_read_b32 v218, v147
	ds_read_b32 v219, v148 offset:65024
	ds_read_b32 v220, v149
	s_add_i32 s58, s77, 1
	s_add_i32 s59, s77, -7
	s_and_b64 s[44:45], s[44:45], exec
	s_cselect_b32 s59, s58, s59
	s_sub_i32 s74, s78, s59
	s_and_b64 s[44:45], s[4:5], exec
	s_cselect_b32 s44, s59, s74
	s_cmpk_gt_u32 s58, 0x206
	v_lshl_add_u32 v222, s44, 5, v169
	v_mov_b32_e32 v221, s89
	ds_read_b32 v172, v221
	ds_read_b128 v[98:101], v170 offset:54272
	ds_read_b128 v[102:105], v151
	ds_read_b128 v[168:171], v151 offset:16
	s_waitcnt lgkmcnt(4)
	v_add_f32_e32 v216, v216, v217
	v_add_f32_e32 v218, v218, v219
	v_max_f32_e32 v220, v220, v220
	v_max_f32_e64 v218, |v218|, v220
	v_rcp_f32_e32 v218, v218
	v_ashrrev_i32_e32 v223, 31, v222
	v_lshlrev_b64 v[222:223], 11, v[222:223]
	v_mul_f32_e32 v216, v216, v218
	v_lshl_add_u64 v[222:223], v[106:107], 0, v[222:223]
	v_cvt_pk_bf16_f32 v220, v216, v17
	global_store_short v[222:223], v220, off
	ds_read_b64_tr_b16 v[180:181], v178 offset:16896
	ds_read_b64_tr_b16 v[182:183], v178 offset:19008
	ds_read_b64_tr_b16 v[184:185], v178 offset:16928
	ds_read_b64_tr_b16 v[186:187], v178 offset:19040
	ds_read_b64_tr_b16 v[188:189], v178 offset:16960
	ds_read_b64_tr_b16 v[190:191], v178 offset:19072
	ds_read_b64_tr_b16 v[192:193], v178 offset:16992
	ds_read_b64_tr_b16 v[194:195], v178 offset:19104
	s_waitcnt lgkmcnt(8)
	v_lshlrev_b32_e32 v173, 16, v98
	v_add_f32_e32 v103, v172, v103
	v_mul_f32_e32 v103, 0x3fb8aa3b, v103
	v_exp_f32_e32 v103, v103
	v_add_f32_e32 v102, v172, v102
	v_mul_f32_e32 v102, 0x3fb8aa3b, v102
	v_and_b32_e32 v98, 0xffff0000, v98
	v_exp_f32_e32 v102, v102
	v_mul_f32_e32 v98, v103, v98
	v_add_f32_e32 v103, v172, v104
	v_mul_f32_e32 v103, 0x3fb8aa3b, v103
	v_exp_f32_e32 v103, v103
	v_mul_f32_e32 v102, v102, v173
	v_cvt_pk_bf16_f32 v98, v102, v98
	v_lshlrev_b32_e32 v102, 16, v99
	v_mul_f32_e32 v102, v103, v102
	v_add_f32_e32 v103, v172, v105
	v_mul_f32_e32 v103, 0x3fb8aa3b, v103
	v_exp_f32_e32 v103, v103
	v_and_b32_e32 v99, 0xffff0000, v99
	v_mul_f32_e32 v16, 0x3fb8aa3b, v172
	v_exp_f32_e32 v16, v16
	v_mul_f32_e32 v99, v103, v99
	v_add_f32_e32 v103, v172, v168
	v_mul_f32_e32 v103, 0x3fb8aa3b, v103
	v_exp_f32_e32 v103, v103
	v_cvt_pk_bf16_f32 v99, v102, v99
	v_lshlrev_b32_e32 v102, 16, v100
	v_and_b32_e32 v100, 0xffff0000, v100
	v_mul_f32_e32 v102, v103, v102
	v_add_f32_e32 v103, v172, v169
	v_mul_f32_e32 v103, 0x3fb8aa3b, v103
	v_exp_f32_e32 v103, v103
	v_pk_mul_f32 v[96:97], v[96:97], v[16:17] op_sel_hi:[1,0]
	v_pk_mul_f32 v[94:95], v[94:95], v[16:17] op_sel_hi:[1,0]
	v_pk_mul_f32 v[92:93], v[92:93], v[16:17] op_sel_hi:[1,0]
	v_mul_f32_e32 v100, v103, v100
	v_add_f32_e32 v103, v172, v170
	v_mul_f32_e32 v103, 0x3fb8aa3b, v103
	v_exp_f32_e32 v103, v103
	v_cvt_pk_bf16_f32 v100, v102, v100
	v_lshlrev_b32_e32 v102, 16, v101
	v_and_b32_e32 v101, 0xffff0000, v101
	v_mul_f32_e32 v102, v103, v102
	v_add_f32_e32 v103, v172, v171
	v_mul_f32_e32 v103, 0x3fb8aa3b, v103
	v_exp_f32_e32 v103, v103
	v_pk_mul_f32 v[90:91], v[90:91], v[16:17] op_sel_hi:[1,0]
	v_pk_mul_f32 v[88:89], v[88:89], v[16:17] op_sel_hi:[1,0]
	v_pk_mul_f32 v[86:87], v[86:87], v[16:17] op_sel_hi:[1,0]
	v_mul_f32_e32 v101, v103, v101
	v_cvt_pk_bf16_f32 v101, v102, v101
	v_pk_mul_f32 v[84:85], v[84:85], v[16:17] op_sel_hi:[1,0]
	v_pk_mul_f32 v[82:83], v[82:83], v[16:17] op_sel_hi:[1,0]
	s_waitcnt lgkmcnt(0)
	s_barrier
	s_nop 1
	v_mfma_f32_16x16x32_bf16 v[94:97], v[180:183], v[98:101], v[94:97]
	v_mfma_f32_16x16x32_bf16 v[90:93], v[184:187], v[98:101], v[90:93]
	v_mfma_f32_16x16x32_bf16 v[86:89], v[188:191], v[98:101], v[86:89]
	v_mfma_f32_16x16x32_bf16 v[82:85], v[192:195], v[98:101], v[82:85]
	s_cbranch_scc1 .LBB0_805
	s_and_saveexec_b64 s[44:45], s[10:11]
	s_cbranch_execz .Lmc1_skip
	s_waitcnt vmcnt(2)
	v_mov_b32_e32 v16, v34
	s_and_b64 vcc, exec, s[4:5]
	s_cbranch_vccz .Lmg_rev1
	s_nop 1
	v_add_f32_dpp v16, v16, v16 row_shr:1 row_mask:0xf bank_mask:0xf bound_ctrl:1
	s_nop 1
	v_add_f32_dpp v16, v16, v16 row_shr:2 row_mask:0xf bank_mask:0xf bound_ctrl:1
	s_nop 1
	v_add_f32_dpp v16, v16, v16 row_shr:4 row_mask:0xf bank_mask:0xf bound_ctrl:1
	s_nop 1
	v_add_f32_dpp v16, v16, v16 row_shr:8 row_mask:0xf bank_mask:0xf bound_ctrl:1
	s_nop 1
	v_add_f32_dpp v16, v16, v16 row_bcast:15 row_mask:0xa bank_mask:0xf
	s_branch .Lmg_done1

.Lmc1_skip:
	s_or_b64 exec, exec, s[44:45]
	s_waitcnt vmcnt(9)
	ds_write_b128 v155, v[0:3]
	s_waitcnt vmcnt(8)
	ds_write_b128 v156, v[4:7]
	s_waitcnt vmcnt(7)
	ds_write_b128 v157, v[8:11]
	s_waitcnt vmcnt(6)
	ds_write_b128 v158, v[12:15]
	s_waitcnt vmcnt(5)
	ds_write_b128 v159, v[22:25]
	s_waitcnt vmcnt(4)
	ds_write_b128 v160, v[30:33]
	s_waitcnt vmcnt(3)
	ds_write_b128 v161, v[38:41]
	s_waitcnt vmcnt(2)
	ds_write_b128 v177, v[42:45]
	s_branch .LBB0_804
